# mixer-A near and far unit epilogues: dwordx2 stores widened to dwordx4 via v_permlane32_swap pairs
# baseline (speedup 1.0000x reference)
; DI unsigned pack2(float lo, float hi) { f32x2_t v = {lo, hi}; return __builtin_bit_cast(unsigned, __builtin_convertvector(v, bf16x2_t)); }
; template <int MODE, int NQ, int TS, bool FAST = false> ...
;     ...
;   if (MODE == 3) {
; #pragma unroll
;     for (int nq = 0; nq < NQ; ++nq) {
;       const float lt = l[nq] + __shfl_xor(l[nq], 32);
;       const size_t tok = (size_t)(seq_base + TS * (q0w + 32 * nq + r32));
;       bf16_t* po = part_o + tok * 512 + ooff + 4 * hh; float* pm = part_ml + (tok * 8 + (ooff >> 6)) * 2;
;       if (hh == 0) { pm[0] = m2[nq]; pm[1] = lt; }
; #pragma unroll
;       for (int g = 0; g < 4; ++g) {
;         uint2 a, b;
;         a.x = pack2(o[nq][0][4 * g], o[nq][0][4 * g + 1]); a.y = pack2(o[nq][0][4 * g + 2], o[nq][0][4 * g + 3]);
;         b.x = pack2(o[nq][1][4 * g], o[nq][1][4 * g + 1]); b.y = pack2(o[nq][1][4 * g + 2], o[nq][1][4 * g + 3]);
;         *(uint2*)(po + 8 * g) = a; *(uint2*)(po + 32 + 8 * g) = b;
;       }
;     }
;     return;
.LBB0_252:
	s_or_b64 exec, exec, s[0:1]
	v_lshlrev_b64 v[2:3], 10, v[96:97]
	v_lshl_add_u64 v[2:3], s[22:23], 0, v[2:3]
	v_lshl_add_u64 v[2:3], s[40:41], 1, v[2:3]
	s_waitcnt lgkmcnt(0)
	v_lshlrev_b32_e32 v0, 4, v105
	v_lshl_add_u64 v[2:3], v[2:3], 0, v[0:1]
	v_cvt_pk_bf16_f32 v32, v32, v33
	v_cvt_pk_bf16_f32 v33, v34, v35
	v_cvt_pk_bf16_f32 v34, v36, v37
	v_cvt_pk_bf16_f32 v35, v38, v39
	v_cvt_pk_bf16_f32 v36, v40, v41
	v_cvt_pk_bf16_f32 v37, v42, v43
	v_cvt_pk_bf16_f32 v38, v44, v45
	v_cvt_pk_bf16_f32 v39, v46, v47
	v_cvt_pk_bf16_f32 v16, v16, v17
	v_cvt_pk_bf16_f32 v17, v18, v19
	v_cvt_pk_bf16_f32 v18, v20, v21
	v_cvt_pk_bf16_f32 v19, v22, v23
	v_cvt_pk_bf16_f32 v20, v24, v25
	v_cvt_pk_bf16_f32 v21, v26, v27
	v_cvt_pk_bf16_f32 v22, v28, v29
	v_cvt_pk_bf16_f32 v23, v30, v31
	s_nop 1
	v_permlane32_swap_b32 v32, v34
	v_permlane32_swap_b32 v33, v35
	v_permlane32_swap_b32 v36, v38
	v_permlane32_swap_b32 v37, v39
	v_permlane32_swap_b32 v16, v18
	v_permlane32_swap_b32 v17, v19
	v_permlane32_swap_b32 v20, v22
	v_permlane32_swap_b32 v21, v23
	s_nop 1
	global_store_dwordx4 v[2:3], v[32:35], off
	global_store_dwordx4 v[2:3], v[36:39], off offset:32
	global_store_dwordx4 v[2:3], v[16:19], off offset:64
	global_store_dwordx4 v[2:3], v[20:23], off offset:96
	s_add_i32 s4, s4, s3
	s_cmpk_lt_i32 s4, 0x400
	s_cbranch_scc0 .LBB0_309

; DI unsigned pack2(float lo, float hi) { f32x2_t v = {lo, hi}; return __builtin_bit_cast(unsigned, __builtin_convertvector(v, bf16x2_t)); }
; template <int MODE, int NQ, int TS, bool FAST = false> ...
;     ...
; #pragma unroll
;   for (int nq = 0; nq < NQ; ++nq) {
;     float lt = l[nq] + __shfl_xor(l[nq], 32);
;     if (MODE == 2) lt += __builtin_amdgcn_exp2f(sink2 - m2[nq]);
;     const float inv = 1.f / lt;
;     bf16_t* op = cat + (size_t)(seq_base + q0w + 32 * nq + r32) * DM + ooff + 4 * hh;
; #pragma unroll
;     for (int g = 0; g < 4; ++g) {
;       uint2 a, b;
;       a.x = pack2(o[nq][0][4 * g] * inv, o[nq][0][4 * g + 1] * inv); a.y = pack2(o[nq][0][4 * g + 2] * inv, o[nq][0][4 * g + 3] * inv);
;       b.x = pack2(o[nq][1][4 * g] * inv, o[nq][1][4 * g + 1] * inv); b.y = pack2(o[nq][1][4 * g + 2] * inv, o[nq][1][4 * g + 3] * inv);
;       *(uint2*)(op + 8 * g) = a; *(uint2*)(op + 32 + 8 * g) = b;
;     }
;   }
.LBB0_415:
	s_or_b64 exec, exec, s[26:27]
	v_lshlrev_b64 v[34:35], 11, v[82:83]
	v_lshl_add_u64 v[34:35], s[64:65], 0, v[34:35]
	v_lshl_add_u64 v[34:35], v[34:35], 0, s[76:77]
	v_lshlrev_b32_e32 v0, 1, v95
	v_lshl_add_u64 v[34:35], v[34:35], 0, v[0:1]
	ds_bpermute_b32 v0, v163, v92
	s_waitcnt vmcnt(0)
	s_barrier
	s_waitcnt lgkmcnt(0)
	v_add_f32_e32 v0, v92, v0
	v_div_scale_f32 v36, s[0:1], v0, v0, 1.0
	v_rcp_f32_e32 v37, v36
	s_mov_b64 s[0:1], 0
	v_fma_f32 v38, -v36, v37, 1.0
	v_fmac_f32_e32 v37, v38, v37
	v_div_scale_f32 v38, vcc, 1.0, v0, 1.0
	v_mul_f32_e32 v39, v38, v37
	v_fma_f32 v40, -v36, v39, v38
	v_fmac_f32_e32 v39, v40, v37
	v_fma_f32 v36, -v36, v39, v38
	v_div_fmas_f32 v36, v36, v37, v39
	v_div_fixup_f32 v36, v36, v0, 1.0
	v_and_b32_e32 v38, 32, v223
	v_lshrrev_b32_e32 v38, 2, v38
	v_mov_b32_e32 v39, 0
	v_lshl_add_u64 v[34:35], v[34:35], 0, v[38:39]
	v_pk_mul_f32 v[18:19], v[18:19], v[36:37] op_sel_hi:[1,0]
	v_pk_mul_f32 v[20:21], v[20:21], v[36:37] op_sel_hi:[1,0]
	v_pk_mul_f32 v[22:23], v[22:23], v[36:37] op_sel_hi:[1,0]
	v_pk_mul_f32 v[24:25], v[24:25], v[36:37] op_sel_hi:[1,0]
	v_pk_mul_f32 v[26:27], v[26:27], v[36:37] op_sel_hi:[1,0]
	v_pk_mul_f32 v[28:29], v[28:29], v[36:37] op_sel_hi:[1,0]
	v_pk_mul_f32 v[30:31], v[30:31], v[36:37] op_sel_hi:[1,0]
	v_pk_mul_f32 v[32:33], v[32:33], v[36:37] op_sel_hi:[1,0]
	v_pk_mul_f32 v[2:3], v[2:3], v[36:37] op_sel_hi:[1,0]
	v_pk_mul_f32 v[4:5], v[4:5], v[36:37] op_sel_hi:[1,0]
	v_pk_mul_f32 v[6:7], v[6:7], v[36:37] op_sel_hi:[1,0]
	v_pk_mul_f32 v[8:9], v[8:9], v[36:37] op_sel_hi:[1,0]
	v_pk_mul_f32 v[10:11], v[10:11], v[36:37] op_sel_hi:[1,0]
	v_pk_mul_f32 v[12:13], v[12:13], v[36:37] op_sel_hi:[1,0]
	v_pk_mul_f32 v[14:15], v[14:15], v[36:37] op_sel_hi:[1,0]
	v_pk_mul_f32 v[16:17], v[16:17], v[36:37] op_sel_hi:[1,0]
	v_cvt_pk_bf16_f32 v18, v18, v19
	v_cvt_pk_bf16_f32 v19, v20, v21
	v_cvt_pk_bf16_f32 v20, v22, v23
	v_cvt_pk_bf16_f32 v21, v24, v25
	v_cvt_pk_bf16_f32 v22, v26, v27
	v_cvt_pk_bf16_f32 v23, v28, v29
	v_cvt_pk_bf16_f32 v24, v30, v31
	v_cvt_pk_bf16_f32 v25, v32, v33
	v_cvt_pk_bf16_f32 v2, v2, v3
	v_cvt_pk_bf16_f32 v3, v4, v5
	v_cvt_pk_bf16_f32 v4, v6, v7
	v_cvt_pk_bf16_f32 v5, v8, v9
	v_cvt_pk_bf16_f32 v6, v10, v11
	v_cvt_pk_bf16_f32 v7, v12, v13
	v_cvt_pk_bf16_f32 v8, v14, v15
	v_cvt_pk_bf16_f32 v9, v16, v17
	s_nop 1
	v_permlane32_swap_b32 v18, v20
	v_permlane32_swap_b32 v19, v21
	v_permlane32_swap_b32 v22, v24
	v_permlane32_swap_b32 v23, v25
	v_permlane32_swap_b32 v2, v4
	v_permlane32_swap_b32 v3, v5
	v_permlane32_swap_b32 v6, v8
	v_permlane32_swap_b32 v7, v9
	s_nop 1
	global_store_dwordx4 v[34:35], v[18:21], off
	global_store_dwordx4 v[34:35], v[22:25], off offset:32
	global_store_dwordx4 v[34:35], v[2:5], off offset:64
	global_store_dwordx4 v[34:35], v[6:9], off offset:96
	v_readlane_b32 s0, v255, 39
	s_add_i32 s81, s81, s3
	s_add_i32 s80, s80, s0
	s_cmpk_gt_i32 s81, 0x5ff
	s_cbranch_scc1 .LBB0_447
	s_branch .LBB0_366
